# phase 3 chunk attention: output-gate rows of the first row group loaded at item start instead of in the epilogue
# speedup vs baseline: 1.0091x; 1.0036x over previous
; DI void attn_block2(const Params& p, int bh, int cp, char* lds) {
;     ...
;     const int b = bh >> 3, h = bh & 7, c0 = 2 * cp, cq = c0 + (wave >> 1);
;     const int qposA = (wave & 1) * 32 + (lane & 15); const int qrowA = b * 8192 + cq * 64 + qposA;
;     float* tab = (float*)(lds + 49152);
;     __syncthreads();
;     for (int i = tid; i < 257; i += 256) tab[i] = p.relb[h * 257 + i] * LOG2E;
;     QG A, B;
;     { const u16* qp = proj + (size_t)qrowA * NC + C_Q + h * 64 + 8 * (lane >> 4); A.q0 = *(const bf16x8*)qp; A.q1 = *(const bf16x8*)(qp + 32);
;       const u16* qb = qp + (size_t)16 * NC; B.q0 = *(const bf16x8*)qb; B.q1 = *(const bf16x8*)(qb + 32); }
;     A.m = -INFINITY; A.l = 0.f; B.m = -INFINITY; B.l = 0.f;
; #pragma unroll
;     for (int dt = 0; dt < 4; ++dt) { A.o[dt] = (f32x4){0.f, 0.f, 0.f, 0.f}; B.o[dt] = (f32x4){0.f, 0.f, 0.f, 0.f}; }
;     unsigned soff[2];
; #pragma unroll
;     for (int i = 0; i < 2; ++i) { const int row = 8 * (i * 4 + wave) + (lane >> 3); const int ch = (lane & 7) ^ ((row >> 1) & 7); soff[i] = (unsigned)(row * NC + ch * 8); }
;     const u16* kbase = proj + (size_t)(b * 8192) * NC + h * 64;
;     ...
;     const int lo = c0 >= 8 ? c0 - 8 : 0, hi = c0 + 1;
;     __syncthreads();
;     ASTAGE2(0, lo); ASTAGE2(1, lo + 1);
;     int buf = 0;
;     for (int kc = lo; kc <= hi; ++kc) {
;         if (kc < hi) asm volatile("s_waitcnt vmcnt(4) lgkmcnt(0)" ::: "memory"); else asm volatile("s_waitcnt vmcnt(0) lgkmcnt(0)" ::: "memory");
;         __builtin_amdgcn_s_barrier();
;         asm volatile("" ::: "memory");
;         const int nb2 = buf >= 1 ? buf - 1 : 2;
;         if (kc + 2 <= hi) ASTAGE2(nb2, kc + 2);
.LBB0_396:
	s_or_b64 exec, exec, s[6:7]
	s_sub_i32 s3, s33, 32
	s_and_b32 s2, s3, -2
	s_ashr_i32 s30, s4, 6
	s_sub_i32 s36, 0x7e, s2
	s_ashr_i32 s6, s4, 7
	s_add_i32 s4, s6, s36
	s_lshl_b32 s7, s30, 5
	s_and_b32 s7, s7, 32
	v_and_b32_e32 v2, 15, v82
	s_lshl_b32 s4, s4, 6
	v_or_b32_e32 v3, s7, v2
	s_add_i32 s4, s4, s83
	v_or_b32_e32 v83, s4, v3
	v_mov_b64_e32 v[4:5], s[68:69]
	v_mad_i64_i32 v[4:5], s[28:29], v83, s43, v[4:5]
	s_lshl_b32 s4, s88, 7
	v_lshl_add_u64 v[4:5], v[4:5], 0, s[4:5]
	v_and_b32_e32 v158, 48, v82
	v_lshl_add_u64 v[4:5], v[4:5], 0, v[158:159]
	s_mov_b32 s28, 0x21000
	global_load_dwordx4 v[18:21], v[4:5], off
	global_load_dwordx4 v[22:25], v[4:5], off offset:64
	v_add_co_u32_e32 v4, vcc, s28, v4
	v_bfe_u32 v3, v82, 3, 3
	s_nop 0
	v_addc_co_u32_e32 v5, vcc, 0, v5, vcc
	v_lshl_or_b32 v3, s30, 3, v3
	s_movk_i32 s28, 0x1080
	s_add_u32 s4, s86, s4
	global_load_dwordx4 v[26:29], v[4:5], off
	global_load_dwordx4 v[30:33], v[4:5], off offset:64
	v_mad_i64_i32 v[246:247], vcc, v83, s43, 0
	s_mul_i32 s100, s88, 0x80
	v_and_b32_e32 v248, 63, v82
	s_mov_b32 s101, 0
	v_lshl_add_u64 v[246:247], s[54:55], 0, v[246:247]
	v_lshrrev_b32_e32 v248, 1, v248
	v_mov_b32_e32 v249, 0
	v_and_b32_e32 v248, 24, v248
	v_lshl_add_u64 v[246:247], v[246:247], 0, s[100:101]
	v_lshl_add_u64 v[246:247], v[246:247], 0, v[248:249]
	v_lshl_add_u64 v[246:247], v[246:247], 0, s[12:13]
	global_load_dwordx2 v[238:239], v[246:247], off offset:32
	global_load_dwordx2 v[240:241], v[246:247], off offset:64
	global_load_dwordx2 v[242:243], v[246:247], off offset:96
	global_load_dwordx2 v[244:245], v[246:247], off
	v_lshrrev_b32_e32 v4, 1, v3
	v_mul_lo_u32 v3, v3, s28
	s_addc_u32 s37, s87, 0
	s_sub_i32 s28, 0x76, s2
	s_cmpk_lt_u32 s3, 0x78
	s_cselect_b32 s89, s28, 0
	s_mul_i32 s28, s89, 0x42000
	v_xor_b32_e32 v4, v4, v82
	s_ashr_i32 s29, s28, 31
	v_lshlrev_b32_e32 v4, 3, v4
	s_lshl_b64 s[28:29], s[28:29], 1
	v_and_or_b32 v158, v4, 56, v3
	s_add_u32 s28, s4, s28
	s_addc_u32 s29, s37, s29
	s_lshl_b32 s30, s30, 10
	v_lshlrev_b64 v[4:5], 1, v[158:159]
	v_lshl_add_u64 v[6:7], s[28:29], 0, v[4:5]
	s_add_i32 s90, s30, 0
	v_lshl_add_u64 v[8:9], v[6:7], 0, s[0:1]
	s_mov_b32 m0, s90
	v_add_u32_e32 v84, 0x21000, v158
	s_waitcnt lgkmcnt(0)
	s_barrier
	global_load_lds_dwordx4 v[8:9], off
	v_lshl_add_u64 v[6:7], v[6:7], 0, s[8:9]
	s_add_i32 m0, s90, 0x6000
	v_mov_b32_e32 v85, v159
	global_load_lds_dwordx4 v[6:7], off
	v_lshlrev_b64 v[6:7], 1, v[84:85]
	v_lshl_add_u64 v[8:9], s[28:29], 0, v[6:7]
	v_lshl_add_u64 v[10:11], v[8:9], 0, s[0:1]
	s_add_i32 m0, s90, 0x1000
	v_lshl_add_u64 v[8:9], v[8:9], 0, s[8:9]
	global_load_lds_dwordx4 v[10:11], off
	s_add_i32 m0, s90, 0x7000
	s_add_u32 s28, s28, 0x84000
	s_addc_u32 s29, s29, 0
	v_lshl_add_u64 v[4:5], s[28:29], 0, v[4:5]
	global_load_lds_dwordx4 v[8:9], off
	v_lshl_add_u64 v[8:9], v[4:5], 0, s[0:1]
	s_add_i32 m0, s90, 0x2000
	v_lshl_add_u64 v[4:5], v[4:5], 0, s[8:9]
	global_load_lds_dwordx4 v[8:9], off
	s_add_i32 m0, s90, 0x8000
	s_sub_i32 s91, 0x7f, s2
	global_load_lds_dwordx4 v[4:5], off
	v_lshl_add_u64 v[4:5], s[28:29], 0, v[6:7]
	v_lshl_add_u64 v[6:7], v[4:5], 0, s[0:1]
	s_add_i32 m0, s90, 0x3000
	v_lshl_add_u64 v[4:5], v[4:5], 0, s[8:9]
	global_load_lds_dwordx4 v[6:7], off
	s_add_i32 m0, s90, 0x9000
	v_and_b32_e32 v106, 63, v82
	global_load_lds_dwordx4 v[4:5], off
	s_cmp_le_i32 s89, s91
	s_mov_b32 s92, 0
	s_cbranch_scc0 .LBB0_416
	ds_read_b32 v207, v159 offset:50176
	v_lshrrev_b32_e32 v4, 4, v106
	v_bfe_u32 v5, v82, 1, 3
	v_lshrrev_b32_e32 v3, 1, v82
	v_bitop3_b32 v5, v4, v5, 4 bitop3:0x36
	s_lshl_b32 s28, s6, 6
	v_bitop3_b32 v6, v3, v4, 7 bitop3:0x6c
	v_lshlrev_b32_e32 v108, 4, v5
	v_lshlrev_b32_e32 v4, 2, v4
	v_lshrrev_b32_e32 v5, 2, v2
	s_or_b32 s7, s28, s7
	v_lshlrev_b32_e32 v107, 4, v6
	v_lshlrev_b32_e32 v6, 3, v106
	v_or_b32_e32 v5, v4, v5
	s_addk_i32 s7, 0x1f90
	v_and_b32_e32 v6, 8, v6
	v_lshlrev_b32_e32 v110, 7, v5
	v_lshrrev_b32_e32 v5, 1, v5
	v_lshl_add_u32 v115, v2, 7, 0
	v_add_u32_e32 v2, s7, v2
	v_add_u32_e32 v109, 0, v6
	v_bfe_u32 v6, v82, 1, 1
	v_bitop3_b32 v3, v5, v3, 1 bitop3:0x78
	v_sub_u32_e32 v2, v2, v4
	s_lshl_b32 s7, s89, 6
	s_lshl_b32 s3, s3, 6
	v_lshlrev_b32_e32 v111, 4, v3
	v_bitop3_b32 v3, v5, v6, 2 bitop3:0x1e
	v_subrev_u32_e32 v2, s7, v2
	s_and_b32 s3, s3, 0xffffff80
	v_lshlrev_b32_e32 v112, 4, v3
	v_bitop3_b32 v3, v5, v6, 4 bitop3:0x1e
	v_subrev_u32_e32 v116, s3, v2
	s_sub_i32 s3, s6, s89
	v_lshlrev_b32_e32 v113, 4, v3
	v_bitop3_b32 v3, v5, v6, 6 bitop3:0x1e
	s_sub_i32 s2, s3, s2
	v_mov_b32_e32 v14, 0
	v_lshlrev_b32_e32 v114, 4, v3
	s_add_i32 s93, s2, 0x7e
	s_add_i32 s94, s7, 0x80
	v_mov_b32_e32 v118, 0xff800000
	v_mov_b32_e32 v117, 0xff800000
	v_mov_b32_e32 v15, v14
	v_mov_b32_e32 v16, v14
	v_mov_b32_e32 v17, v14
	v_mov_b32_e32 v10, v14
	v_mov_b32_e32 v11, v14
	v_mov_b32_e32 v12, v14
	v_mov_b32_e32 v13, v14
	v_mov_b32_e32 v6, v14
	v_mov_b32_e32 v7, v14
	v_mov_b32_e32 v8, v14
	v_mov_b32_e32 v9, v14
	v_mov_b32_e32 v2, v14
	v_mov_b32_e32 v3, v14
	v_mov_b32_e32 v4, v14
	v_mov_b32_e32 v5, v14
	v_mov_b32_e32 v46, v14
	v_mov_b32_e32 v47, v14
	v_mov_b32_e32 v48, v14
	v_mov_b32_e32 v49, v14
	v_mov_b32_e32 v38, v14
	v_mov_b32_e32 v39, v14
	v_mov_b32_e32 v40, v14
	v_mov_b32_e32 v41, v14
	v_mov_b32_e32 v42, v14
	v_mov_b32_e32 v43, v14
	v_mov_b32_e32 v44, v14
	v_mov_b32_e32 v45, v14
	v_mov_b32_e32 v34, v14
	v_mov_b32_e32 v35, v14
	v_mov_b32_e32 v36, v14
	v_mov_b32_e32 v37, v14
	v_mov_b32_e32 v86, v14
	v_mov_b32_e32 v87, v14
	s_branch .LBB0_400

; DI unsigned pack2(float lo, float hi) { f32x2_t v = {lo, hi}; bf16x2_t b = __builtin_convertvector(v, bf16x2_t); return __builtin_bit_cast(unsigned, b); }
; DI float bflo(unsigned u) { return __uint_as_float(u << 16); }
; DI float bfhi(unsigned u) { return __uint_as_float(u & 0xffff0000u); }
; DI float rcpf_(float x) { return __builtin_amdgcn_rcpf(x); }
; DI float silu(float x) { return x * rcpf_(1.f + __expf(-x)); }
; DI float xadd16(float v) { const unsigned x = __float_as_uint(v); auto r = __builtin_amdgcn_permlane16_swap(x, x, false, false); return __uint_as_float(r[0]) + __uint_as_float(r[1]); }
; DI float xadd32(float v) { const unsigned x = __float_as_uint(v); auto r = __builtin_amdgcn_permlane32_swap(x, x, false, false); return __uint_as_float(r[0]) + __uint_as_float(r[1]); }
; DI void attn_finish(const Params& p, float l, const f32x4 (&o)[4], int qrow, int h, int lane) {
;     const int g = lane >> 4; const u16* proj = (const u16*)(p.ws + W_PROJ);
;     l = xadd16(l); l = xadd32(l);
;     const float inv = rcpf_(l);
;     u16* z = (u16*)(p.ws + W_XB) + (size_t)qrow * DM + h * 64; const u16* ga = proj + (size_t)qrow * NC + C_GA + h * 64;
;     uint2 w[4];
; #pragma unroll
;     for (int dt = 0; dt < 4; ++dt) { const int d = 16 * dt + 4 * g; const uint2 gg = *(const uint2*)(ga + d);
;         w[dt].x = pack2(o[dt][0] * inv * silu(bflo(gg.x)), o[dt][1] * inv * silu(bfhi(gg.x))); w[dt].y = pack2(o[dt][2] * inv * silu(bflo(gg.y)), o[dt][3] * inv * silu(bfhi(gg.y))); }
; #pragma unroll
;     for (int dt = 0; dt < 4; dt += 2) *(uint4*)(z + 16 * (dt + (g & 1)) + 8 * (g >> 1)) = widen16(w[dt], w[dt + 1]);
; DI void attn_block2(const Params& p, int bh, int cp, char* lds) {
;     ...
;     attn_finish(p, A.l, A.o, qrowA, h, lane);
;     attn_finish(p, B.l, B.o, qrowA + 16, h, lane);
.LBB0_417:
	s_waitcnt vmcnt(0)
	v_mad_i64_i32 v[18:19], s[2:3], v83, s43, 0
	s_lshl_b32 s2, s88, 6
	v_mov_b32_e32 v28, v67
	v_lshl_add_u64 v[18:19], s[54:55], 0, v[18:19]
	s_lshl_b32 s4, s2, 1
	v_lshrrev_b32_e32 v62, 1, v106
	v_permlane16_swap_b32_e32 v67, v28
	v_lshl_add_u64 v[20:21], v[18:19], 0, s[4:5]
	v_and_b32_e32 v158, 24, v62
	v_add_f32_e32 v28, v67, v28
	v_lshl_add_u64 v[20:21], v[20:21], 0, v[158:159]
	v_mov_b32_e32 v29, v28
	v_lshl_add_u64 v[22:23], v[20:21], 0, s[12:13]
	v_add_co_u32_e32 v20, vcc, 0x2bf5000, v20
	v_permlane32_swap_b32_e32 v28, v29
	s_nop 0
	v_addc_co_u32_e32 v21, vcc, 0, v21, vcc
	v_add_f32_e32 v28, v28, v29
	v_mov_b32_e32 v24, v238
	v_mov_b32_e32 v25, v239
	v_mov_b32_e32 v26, v240
	v_mov_b32_e32 v27, v241
	v_rcp_f32_e32 v30, v28
	v_mov_b32_e32 v28, v242
	v_mov_b32_e32 v29, v243
	v_mad_i64_i32 v[18:19], s[2:3], v83, s70, v[18:19]
	v_mov_b32_e32 v20, v244
	v_mov_b32_e32 v21, v245
	v_pk_mul_f32 v[22:23], v[34:35], v[30:31] op_sel_hi:[1,0]
	v_pk_mul_f32 v[32:33], v[36:37], v[30:31] op_sel_hi:[1,0]
	v_pk_mul_f32 v[34:35], v[42:43], v[30:31] op_sel_hi:[1,0]
	v_pk_mul_f32 v[36:37], v[44:45], v[30:31] op_sel_hi:[1,0]
	v_pk_mul_f32 v[38:39], v[38:39], v[30:31] op_sel_hi:[1,0]
	s_waitcnt vmcnt(0)
	v_and_b32_e32 v43, 0xffff0000, v24
	v_lshlrev_b32_e32 v44, 16, v26
	v_and_b32_e32 v45, 0xffff0000, v26
	v_lshlrev_b32_e32 v50, 16, v27
	v_and_b32_e32 v51, 0xffff0000, v27
	v_lshlrev_b32_e32 v42, 16, v24
	v_lshlrev_b32_e32 v26, 16, v20
	v_and_b32_e32 v27, 0xffff0000, v20
	v_lshlrev_b32_e32 v20, 16, v21
	v_and_b32_e32 v21, 0xffff0000, v21
	v_lshlrev_b32_e32 v24, 16, v25
	v_mul_f32_e32 v52, 0xbfb8aa3b, v43
	v_mul_f32_e32 v57, 0xbfb8aa3b, v50
	v_mul_f32_e32 v58, 0xbfb8aa3b, v51
	v_mul_f32_e32 v59, 0xbfb8aa3b, v26
	v_mul_f32_e32 v60, 0xbfb8aa3b, v27
	v_mul_f32_e32 v61, 0xbfb8aa3b, v20
	v_mul_f32_e32 v63, 0xbfb8aa3b, v21
	v_mul_f32_e32 v53, 0xbfb8aa3b, v24
	v_exp_f32_e32 v52, v52
	v_exp_f32_e32 v64, v57
	v_exp_f32_e32 v65, v58
	v_exp_f32_e32 v57, v59
	v_exp_f32_e32 v58, v60
	v_exp_f32_e32 v59, v61
	v_exp_f32_e32 v60, v63
	v_exp_f32_e32 v53, v53
	v_add_f32_e32 v61, 1.0, v52
	v_add_f32_e32 v70, 1.0, v57
	v_add_f32_e32 v71, 1.0, v58
	v_add_f32_e32 v72, 1.0, v59
	v_add_f32_e32 v73, 1.0, v60
	v_add_f32_e32 v63, 1.0, v53
	v_rcp_f32_e32 v53, v61
	v_rcp_f32_e32 v58, v70
	v_rcp_f32_e32 v59, v71
	v_rcp_f32_e32 v60, v72
	v_rcp_f32_e32 v61, v73
	v_mul_f32_e32 v55, 0xbfb8aa3b, v44
	v_mul_f32_e32 v56, 0xbfb8aa3b, v45
	v_exp_f32_e32 v55, v55
	v_exp_f32_e32 v56, v56
	v_pk_mul_f32 v[26:27], v[58:59], v[26:27]
	v_pk_mul_f32 v[20:21], v[60:61], v[20:21]
	v_mul_f32_e32 v31, 0xbfb8aa3b, v42
	v_pk_mul_f32 v[22:23], v[22:23], v[26:27]
	v_pk_mul_f32 v[20:21], v[32:33], v[20:21]
	v_exp_f32_e32 v31, v31
	v_add_f32_e32 v68, 1.0, v55
	v_add_f32_e32 v69, 1.0, v56
	v_cvt_pk_bf16_f32 v22, v22, v23
	v_cvt_pk_bf16_f32 v23, v20, v21
	v_add_f32_e32 v20, 1.0, v64
	v_add_f32_e32 v21, 1.0, v65
	v_rcp_f32_e32 v56, v68
	v_rcp_f32_e32 v57, v69
	v_rcp_f32_e32 v20, v20
	v_rcp_f32_e32 v21, v21
	v_and_b32_e32 v25, 0xffff0000, v25
	v_mul_f32_e32 v54, 0xbfb8aa3b, v25
	v_exp_f32_e32 v54, v54
	v_add_f32_e32 v31, 1.0, v31
	v_pk_mul_f32 v[44:45], v[56:57], v[44:45]
	v_pk_mul_f32 v[32:33], v[40:41], v[30:31] op_sel_hi:[1,0]
	v_pk_mul_f32 v[20:21], v[20:21], v[50:51]
	v_pk_mul_f32 v[26:27], v[38:39], v[44:45]
	v_pk_mul_f32 v[20:21], v[32:33], v[20:21]
	v_cvt_pk_bf16_f32 v26, v26, v27
	v_cvt_pk_bf16_f32 v27, v20, v21
	v_lshlrev_b32_e32 v20, 16, v28
	v_add_f32_e32 v67, 1.0, v54
	v_mul_f32_e32 v21, 0xbfb8aa3b, v20
	v_rcp_f32_e32 v52, v31
	v_rcp_f32_e32 v54, v63
	v_rcp_f32_e32 v55, v67
	v_exp_f32_e32 v31, v21
	v_and_b32_e32 v21, 0xffff0000, v28
	v_mul_f32_e32 v28, 0xbfb8aa3b, v21
	v_exp_f32_e32 v28, v28
	v_pk_mul_f32 v[24:25], v[54:55], v[24:25]
	v_add_f32_e32 v31, 1.0, v31
	v_pk_mul_f32 v[36:37], v[36:37], v[24:25]
	v_add_f32_e32 v28, 1.0, v28
	v_cvt_pk_bf16_f32 v25, v36, v37
	v_lshlrev_b32_e32 v36, 16, v29
	v_rcp_f32_e32 v33, v28
	v_and_b32_e32 v37, 0xffff0000, v29
	v_mul_f32_e32 v28, 0xbfb8aa3b, v36
	v_exp_f32_e32 v28, v28
	v_mul_f32_e32 v29, 0xbfb8aa3b, v37
	v_rcp_f32_e32 v32, v31
	v_exp_f32_e32 v29, v29
	v_add_f32_e32 v28, 1.0, v28
	v_pk_mul_f32 v[42:43], v[52:53], v[42:43]
	v_pk_mul_f32 v[20:21], v[32:33], v[20:21]
	v_rcp_f32_e32 v32, v28
	v_add_f32_e32 v28, 1.0, v29
	v_rcp_f32_e32 v33, v28
	v_pk_mul_f32 v[34:35], v[34:35], v[42:43]
	v_permlane16_swap_b32_e32 v23, v25
	v_cvt_pk_bf16_f32 v24, v34, v35
	v_pk_mul_f32 v[34:35], v[46:47], v[30:31] op_sel_hi:[1,0]
	s_nop 0
	v_permlane16_swap_b32_e32 v22, v24
	v_pk_mul_f32 v[20:21], v[34:35], v[20:21]
	s_nop 0
	v_cvt_pk_bf16_f32 v28, v20, v21
	v_pk_mul_f32 v[20:21], v[48:49], v[30:31] op_sel_hi:[1,0]
	v_pk_mul_f32 v[30:31], v[32:33], v[36:37]
	v_or_b32_e32 v33, 16, v83
	v_pk_mul_f32 v[20:21], v[20:21], v[30:31]
	v_permlane16_swap_b32_e32 v26, v28
	v_cvt_pk_bf16_f32 v29, v20, v21
	v_lshl_add_u64 v[20:21], v[18:19], 0, s[4:5]
	v_and_b32_e32 v18, 16, v62
	v_mov_b32_e32 v19, v159
	v_lshl_add_u64 v[30:31], v[20:21], 0, v[18:19]
	v_and_b32_e32 v20, 16, v82
	v_lshlrev_b32_e32 v20, 1, v20
	v_mov_b32_e32 v21, v159
	v_lshl_add_u64 v[30:31], v[30:31], 0, v[20:21]
	global_store_dwordx4 v[30:31], v[22:25], off
	v_permlane16_swap_b32_e32 v27, v29
	s_nop 0
	v_mov_b64_e32 v[22:23], s[54:55]
	v_mad_i64_i32 v[22:23], s[2:3], v33, s43, v[22:23]
	v_lshl_add_u64 v[24:25], v[22:23], 0, s[4:5]
	v_lshl_add_u64 v[24:25], v[24:25], 0, v[158:159]
	s_mov_b32 s2, 0x2bf5000
	global_store_dwordx4 v[30:31], v[26:29], off offset:64
	v_mov_b32_e32 v32, v66
	s_nop 1
	v_permlane16_swap_b32_e32 v66, v32
	v_add_co_u32_e32 v26, vcc, s2, v24
	v_add_f32_e32 v32, v66, v32
	s_nop 0
	v_addc_co_u32_e32 v27, vcc, 0, v25, vcc
	global_load_dwordx2 v[26:27], v[26:27], off offset:1024
	v_lshl_add_u64 v[24:25], v[24:25], 0, s[12:13]
	global_load_dwordx2 v[28:29], v[24:25], off offset:32
	global_load_dwordx2 v[30:31], v[24:25], off offset:64
	v_mov_b32_e32 v34, v32
	global_load_dwordx2 v[24:25], v[24:25], off offset:96
	s_nop 0
	v_permlane32_swap_b32_e32 v32, v34
	v_add_f32_e32 v32, v32, v34
	v_rcp_f32_e32 v32, v32
	s_waitcnt vmcnt(0)
; DI unsigned pack2(float lo, float hi) { f32x2_t v = {lo, hi}; bf16x2_t b = __builtin_convertvector(v, bf16x2_t); return __builtin_bit_cast(unsigned, b); }
; DI float bflo(unsigned u) { return __uint_as_float(u << 16); }
; DI float bfhi(unsigned u) { return __uint_as_float(u & 0xffff0000u); }
; DI float rcpf_(float x) { return __builtin_amdgcn_rcpf(x); }
; DI float silu(float x) { return x * rcpf_(1.f + __expf(-x)); }
; DI float xadd16(float v) { const unsigned x = __float_as_uint(v); auto r = __builtin_amdgcn_permlane16_swap(x, x, false, false); return __uint_as_float(r[0]) + __uint_as_float(r[1]); }
; DI float xadd32(float v) { const unsigned x = __float_as_uint(v); auto r = __builtin_amdgcn_permlane32_swap(x, x, false, false); return __uint_as_float(r[0]) + __uint_as_float(r[1]); }
; DI void attn_finish(const Params& p, float l, const f32x4 (&o)[4], int qrow, int h, int lane) {
;     const int g = lane >> 4; const u16* proj = (const u16*)(p.ws + W_PROJ);
;     l = xadd16(l); l = xadd32(l);
;     const float inv = rcpf_(l);
;     u16* z = (u16*)(p.ws + W_XB) + (size_t)qrow * DM + h * 64; const u16* ga = proj + (size_t)qrow * NC + C_GA + h * 64;
;     uint2 w[4];
; #pragma unroll
;     for (int dt = 0; dt < 4; ++dt) { const int d = 16 * dt + 4 * g; const uint2 gg = *(const uint2*)(ga + d);
;         w[dt].x = pack2(o[dt][0] * inv * silu(bflo(gg.x)), o[dt][1] * inv * silu(bfhi(gg.x))); w[dt].y = pack2(o[dt][2] * inv * silu(bflo(gg.y)), o[dt][3] * inv * silu(bfhi(gg.y))); }
; #pragma unroll
;     for (int dt = 0; dt < 4; dt += 2) *(uint4*)(z + 16 * (dt + (g & 1)) + 8 * (g >> 1)) = widen16(w[dt], w[dt + 1]);
	v_lshlrev_b32_e32 v34, 16, v26
	v_mul_f32_e32 v35, 0xbfb8aa3b, v34
	v_exp_f32_e32 v36, v35
	v_and_b32_e32 v35, 0xffff0000, v26
	v_mul_f32_e32 v26, 0xbfb8aa3b, v35
	v_exp_f32_e32 v26, v26
	v_add_f32_e32 v36, 1.0, v36
	v_rcp_f32_e32 v36, v36
	v_pk_mul_f32 v[2:3], v[2:3], v[32:33] op_sel_hi:[1,0]
	v_add_f32_e32 v26, 1.0, v26
	v_rcp_f32_e32 v37, v26
	v_lshlrev_b32_e32 v26, 16, v27
	v_and_b32_e32 v27, 0xffff0000, v27
	v_mul_f32_e32 v38, 0xbfb8aa3b, v26
	v_mul_f32_e32 v39, 0xbfb8aa3b, v27
	v_exp_f32_e32 v38, v38
	v_exp_f32_e32 v39, v39
	v_pk_mul_f32 v[34:35], v[36:37], v[34:35]
	v_pk_mul_f32 v[4:5], v[4:5], v[32:33] op_sel_hi:[1,0]
	v_add_f32_e32 v36, 1.0, v38
	v_add_f32_e32 v37, 1.0, v39
	v_rcp_f32_e32 v36, v36
	v_rcp_f32_e32 v37, v37
	v_pk_mul_f32 v[2:3], v[2:3], v[34:35]
	v_pk_mul_f32 v[6:7], v[6:7], v[32:33] op_sel_hi:[1,0]
	v_cvt_pk_bf16_f32 v2, v2, v3
	v_pk_mul_f32 v[26:27], v[36:37], v[26:27]
	v_pk_mul_f32 v[10:11], v[10:11], v[32:33] op_sel_hi:[1,0]
	v_pk_mul_f32 v[4:5], v[4:5], v[26:27]
	s_nop 0
	v_cvt_pk_bf16_f32 v3, v4, v5
	v_lshlrev_b32_e32 v4, 16, v28
	v_mul_f32_e32 v5, 0xbfb8aa3b, v4
	v_exp_f32_e32 v26, v5
	v_and_b32_e32 v5, 0xffff0000, v28
	v_mul_f32_e32 v27, 0xbfb8aa3b, v5
	v_exp_f32_e32 v27, v27
	v_lshlrev_b32_e32 v28, 16, v29
	v_and_b32_e32 v29, 0xffff0000, v29
	v_add_f32_e32 v26, 1.0, v26
	v_add_f32_e32 v27, 1.0, v27
	v_mul_f32_e32 v34, 0xbfb8aa3b, v28
	v_mul_f32_e32 v35, 0xbfb8aa3b, v29
	v_rcp_f32_e32 v26, v26
	v_rcp_f32_e32 v27, v27
	v_exp_f32_e32 v34, v34
	v_exp_f32_e32 v35, v35
	v_pk_mul_f32 v[4:5], v[26:27], v[4:5]
	v_add_f32_e32 v26, 1.0, v34
	v_add_f32_e32 v27, 1.0, v35
	v_rcp_f32_e32 v26, v26
	v_rcp_f32_e32 v27, v27
	v_pk_mul_f32 v[4:5], v[6:7], v[4:5]
	v_pk_mul_f32 v[6:7], v[8:9], v[32:33] op_sel_hi:[1,0]
	v_cvt_pk_bf16_f32 v4, v4, v5
	v_pk_mul_f32 v[8:9], v[26:27], v[28:29]
	v_lshlrev_b32_e32 v26, 16, v31
	v_pk_mul_f32 v[6:7], v[6:7], v[8:9]
	v_and_b32_e32 v27, 0xffff0000, v31
	v_cvt_pk_bf16_f32 v5, v6, v7
	v_lshlrev_b32_e32 v6, 16, v30
	v_mul_f32_e32 v7, 0xbfb8aa3b, v6
	v_exp_f32_e32 v8, v7
	v_and_b32_e32 v7, 0xffff0000, v30
	v_mul_f32_e32 v9, 0xbfb8aa3b, v7
	v_exp_f32_e32 v9, v9
	v_add_f32_e32 v8, 1.0, v8
	v_mul_f32_e32 v28, 0xbfb8aa3b, v26
	v_mul_f32_e32 v29, 0xbfb8aa3b, v27
	v_add_f32_e32 v9, 1.0, v9
	v_rcp_f32_e32 v8, v8
	v_rcp_f32_e32 v9, v9
	v_exp_f32_e32 v28, v28
	v_exp_f32_e32 v29, v29
	v_permlane16_swap_b32_e32 v2, v4
	v_pk_mul_f32 v[6:7], v[8:9], v[6:7]
	v_add_f32_e32 v8, 1.0, v28
	v_add_f32_e32 v9, 1.0, v29
	v_rcp_f32_e32 v8, v8
	v_rcp_f32_e32 v9, v9
	v_pk_mul_f32 v[6:7], v[10:11], v[6:7]
	v_pk_mul_f32 v[10:11], v[12:13], v[32:33] op_sel_hi:[1,0]
	v_cvt_pk_bf16_f32 v6, v6, v7
	v_pk_mul_f32 v[8:9], v[8:9], v[26:27]
	v_pk_mul_f32 v[12:13], v[14:15], v[32:33] op_sel_hi:[1,0]
	v_pk_mul_f32 v[8:9], v[10:11], v[8:9]
	v_lshlrev_b32_e32 v14, 16, v25
	v_cvt_pk_bf16_f32 v7, v8, v9
	v_lshlrev_b32_e32 v8, 16, v24
	v_mul_f32_e32 v9, 0xbfb8aa3b, v8
	v_exp_f32_e32 v10, v9
	v_and_b32_e32 v9, 0xffff0000, v24
	v_mul_f32_e32 v11, 0xbfb8aa3b, v9
	v_exp_f32_e32 v11, v11
	v_and_b32_e32 v15, 0xffff0000, v25
	v_add_f32_e32 v10, 1.0, v10
	v_mul_f32_e32 v24, 0xbfb8aa3b, v14
	v_add_f32_e32 v11, 1.0, v11
	v_mul_f32_e32 v25, 0xbfb8aa3b, v15
	v_rcp_f32_e32 v10, v10
	v_rcp_f32_e32 v11, v11
	v_exp_f32_e32 v24, v24
	v_exp_f32_e32 v25, v25
	v_permlane16_swap_b32_e32 v3, v5
	v_pk_mul_f32 v[8:9], v[10:11], v[8:9]
	v_add_f32_e32 v10, 1.0, v24
	v_add_f32_e32 v11, 1.0, v25
	v_rcp_f32_e32 v10, v10
	v_rcp_f32_e32 v11, v11
	v_pk_mul_f32 v[8:9], v[12:13], v[8:9]
	v_pk_mul_f32 v[12:13], v[16:17], v[32:33] op_sel_hi:[1,0]
	v_cvt_pk_bf16_f32 v8, v8, v9
	v_pk_mul_f32 v[10:11], v[10:11], v[14:15]
	s_nop 0
	v_permlane16_swap_b32_e32 v6, v8
	v_pk_mul_f32 v[10:11], v[12:13], v[10:11]
	s_nop 0
	v_cvt_pk_bf16_f32 v9, v10, v11
	v_mad_i64_i32 v[10:11], s[2:3], v33, s70, v[22:23]
	v_lshl_add_u64 v[10:11], v[10:11], 0, s[4:5]
	v_lshl_add_u64 v[10:11], v[10:11], 0, v[18:19]
	v_lshl_add_u64 v[10:11], v[10:11], 0, v[20:21]
	v_permlane16_swap_b32_e32 v7, v9
	global_store_dwordx4 v[10:11], v[2:5], off
	global_store_dwordx4 v[10:11], v[6:9], off offset:64
